# adds: alpha_rows rewritten (all loads in flight); even WGs apply branch weights for both 64-row halves, odd WGs (long hf=1 item) skip theirs
# speedup vs baseline: 1.0388x; 1.0121x over previous
.LBB0_816:
	s_or_b64 exec, exec, s[8:9]
	s_waitcnt lgkmcnt(0)
	s_barrier
	ds_read2st64_b32 v[0:1], v246 offset1:1
	s_mov_b32 s0, 0x800000
	v_lshl_add_u64 v[46:47], v[190:191], 0, v[106:107]
	v_mov_b32_e32 v141, v107
	v_lshl_add_u64 v[54:55], v[190:191], 0, v[140:141]
	s_waitcnt lgkmcnt(0)
	v_add_f32_e32 v0, v0, v1
	v_mov_b32_e32 v1, 0x3727c5ac
	v_fmamk_f32 v0, v0, 0x3aaaaaab, v1
	v_cmp_gt_f32_e32 vcc, s0, v0
	v_mul_f32_e32 v1, 0x4b800000, v0
	v_readlane_b32 s68, v254, 5
	v_cndmask_b32_e32 v0, v0, v1, vcc
	v_rsq_f32_e32 v0, v0
	v_readlane_b32 s70, v254, 7
	v_readlane_b32 s12, v255, 3
	s_or_b32 s44, s44, s50
	v_mul_f32_e32 v1, 0x45800000, v0
	v_cndmask_b32_e32 v44, v0, v1, vcc
	global_load_dwordx2 v[52:53], v[46:47], off
	global_load_dwordx4 v[0:3], v[134:135], off
	global_load_dwordx2 v[56:57], v[54:55], off
	global_load_dwordx4 v[4:7], v[134:135], off offset:64
	global_load_dwordx2 v[58:59], v[46:47], off offset:128
	global_load_dwordx4 v[8:11], v[134:135], off offset:256
	global_load_dwordx2 v[60:61], v[46:47], off offset:160
	global_load_dwordx4 v[12:15], v[134:135], off offset:320
	global_load_dwordx2 v[62:63], v[46:47], off offset:256
	global_load_dwordx4 v[16:19], v[134:135], off offset:512
	global_load_dwordx2 v[64:65], v[46:47], off offset:288
	global_load_dwordx4 v[20:23], v[134:135], off offset:576
	global_load_dwordx2 v[66:67], v[46:47], off offset:384
	global_load_dwordx4 v[24:27], v[134:135], off offset:768
	global_load_dwordx2 v[68:69], v[46:47], off offset:416
	global_load_dwordx4 v[28:31], v[134:135], off offset:832
	global_load_dwordx2 v[70:71], v[46:47], off offset:512
	global_load_dwordx4 v[32:35], v[134:135], off offset:1024
	global_load_dwordx2 v[72:73], v[46:47], off offset:544
	global_load_dwordx4 v[36:39], v[134:135], off offset:1088
	global_load_dwordx2 v[74:75], v[46:47], off offset:640
	global_load_dwordx4 v[40:43], v[134:135], off offset:1280
	global_load_dwordx2 v[76:77], v[46:47], off offset:672
	global_load_dwordx4 v[48:51], v[134:135], off offset:1344
	v_readlane_b32 s69, v254, 6
	v_readlane_b32 s71, v254, 8
	v_readlane_b32 s13, v255, 4
	s_waitcnt vmcnt(23)
	v_lshlrev_b32_e32 v78, 16, v52
	v_and_b32_e32 v79, 0xffff0000, v52
	v_lshlrev_b32_e32 v52, 16, v53
	v_and_b32_e32 v53, 0xffff0000, v53
	v_pk_mul_f32 v[78:79], v[44:45], v[78:79] op_sel_hi:[0,1]
	v_pk_mul_f32 v[52:53], v[44:45], v[52:53] op_sel_hi:[0,1]
	s_waitcnt vmcnt(22)
	v_pk_mul_f32 v[0:1], v[0:1], v[78:79]
	v_pk_mul_f32 v[2:3], v[2:3], v[52:53]
	v_cvt_pk_bf16_f32 v0, v0, v1
	v_cvt_pk_bf16_f32 v1, v2, v3
	global_store_dwordx2 v[46:47], v[0:1], off
	s_waitcnt vmcnt(22)
	v_lshlrev_b32_e32 v0, 16, v56
	v_and_b32_e32 v1, 0xffff0000, v56
	v_lshlrev_b32_e32 v2, 16, v57
	v_and_b32_e32 v3, 0xffff0000, v57
	v_pk_mul_f32 v[0:1], v[44:45], v[0:1] op_sel_hi:[0,1]
	v_pk_mul_f32 v[2:3], v[44:45], v[2:3] op_sel_hi:[0,1]
	s_waitcnt vmcnt(21)
	v_pk_mul_f32 v[0:1], v[4:5], v[0:1]
	v_pk_mul_f32 v[2:3], v[6:7], v[2:3]
	v_cvt_pk_bf16_f32 v0, v0, v1
	v_cvt_pk_bf16_f32 v1, v2, v3
	global_store_dwordx2 v[54:55], v[0:1], off
	s_waitcnt vmcnt(21)
	v_lshlrev_b32_e32 v0, 16, v58
	v_and_b32_e32 v1, 0xffff0000, v58
	v_lshlrev_b32_e32 v2, 16, v59
	v_and_b32_e32 v3, 0xffff0000, v59
	v_pk_mul_f32 v[0:1], v[44:45], v[0:1] op_sel_hi:[0,1]
	v_pk_mul_f32 v[2:3], v[44:45], v[2:3] op_sel_hi:[0,1]
	s_waitcnt vmcnt(20)
	v_pk_mul_f32 v[0:1], v[8:9], v[0:1]
	v_pk_mul_f32 v[2:3], v[10:11], v[2:3]
	v_cvt_pk_bf16_f32 v0, v0, v1
	v_cvt_pk_bf16_f32 v1, v2, v3
	global_store_dwordx2 v[46:47], v[0:1], off offset:128
	s_waitcnt vmcnt(20)
	v_lshlrev_b32_e32 v0, 16, v60
	v_and_b32_e32 v1, 0xffff0000, v60
	v_lshlrev_b32_e32 v2, 16, v61
	v_and_b32_e32 v3, 0xffff0000, v61
	v_pk_mul_f32 v[0:1], v[44:45], v[0:1] op_sel_hi:[0,1]
	v_pk_mul_f32 v[2:3], v[44:45], v[2:3] op_sel_hi:[0,1]
	s_waitcnt vmcnt(19)
	v_pk_mul_f32 v[0:1], v[12:13], v[0:1]
	v_pk_mul_f32 v[2:3], v[14:15], v[2:3]
	v_cvt_pk_bf16_f32 v0, v0, v1
	v_cvt_pk_bf16_f32 v1, v2, v3
	global_store_dwordx2 v[46:47], v[0:1], off offset:160
	s_waitcnt vmcnt(19)
	v_lshlrev_b32_e32 v0, 16, v62
	v_and_b32_e32 v1, 0xffff0000, v62
	v_lshlrev_b32_e32 v2, 16, v63
	v_and_b32_e32 v3, 0xffff0000, v63
	v_pk_mul_f32 v[0:1], v[44:45], v[0:1] op_sel_hi:[0,1]
	v_pk_mul_f32 v[2:3], v[44:45], v[2:3] op_sel_hi:[0,1]
	s_waitcnt vmcnt(18)
	v_pk_mul_f32 v[0:1], v[16:17], v[0:1]
	v_pk_mul_f32 v[2:3], v[18:19], v[2:3]
	v_cvt_pk_bf16_f32 v0, v0, v1
	v_cvt_pk_bf16_f32 v1, v2, v3
	global_store_dwordx2 v[46:47], v[0:1], off offset:256
	s_waitcnt vmcnt(18)
	v_lshlrev_b32_e32 v0, 16, v64
	v_and_b32_e32 v1, 0xffff0000, v64
	v_lshlrev_b32_e32 v2, 16, v65
	v_and_b32_e32 v3, 0xffff0000, v65
	v_pk_mul_f32 v[0:1], v[44:45], v[0:1] op_sel_hi:[0,1]
	v_pk_mul_f32 v[2:3], v[44:45], v[2:3] op_sel_hi:[0,1]
	s_waitcnt vmcnt(17)
	v_pk_mul_f32 v[0:1], v[20:21], v[0:1]
	v_pk_mul_f32 v[2:3], v[22:23], v[2:3]
	v_cvt_pk_bf16_f32 v0, v0, v1
	v_cvt_pk_bf16_f32 v1, v2, v3
	global_store_dwordx2 v[46:47], v[0:1], off offset:288
	s_waitcnt vmcnt(17)
	v_lshlrev_b32_e32 v0, 16, v66
	v_and_b32_e32 v1, 0xffff0000, v66
	v_lshlrev_b32_e32 v2, 16, v67
	v_and_b32_e32 v3, 0xffff0000, v67
	v_pk_mul_f32 v[0:1], v[44:45], v[0:1] op_sel_hi:[0,1]
	v_pk_mul_f32 v[2:3], v[44:45], v[2:3] op_sel_hi:[0,1]
	s_waitcnt vmcnt(16)
	v_pk_mul_f32 v[0:1], v[24:25], v[0:1]
	v_pk_mul_f32 v[2:3], v[26:27], v[2:3]
	v_cvt_pk_bf16_f32 v0, v0, v1
	v_cvt_pk_bf16_f32 v1, v2, v3
	global_store_dwordx2 v[46:47], v[0:1], off offset:384
	s_waitcnt vmcnt(16)
	v_lshlrev_b32_e32 v0, 16, v68
	v_and_b32_e32 v1, 0xffff0000, v68
	v_lshlrev_b32_e32 v2, 16, v69
	v_and_b32_e32 v3, 0xffff0000, v69
	v_pk_mul_f32 v[0:1], v[44:45], v[0:1] op_sel_hi:[0,1]
	v_pk_mul_f32 v[2:3], v[44:45], v[2:3] op_sel_hi:[0,1]
	s_waitcnt vmcnt(15)
	v_pk_mul_f32 v[0:1], v[28:29], v[0:1]
	v_pk_mul_f32 v[2:3], v[30:31], v[2:3]
	v_cvt_pk_bf16_f32 v0, v0, v1
	v_cvt_pk_bf16_f32 v1, v2, v3
	global_store_dwordx2 v[46:47], v[0:1], off offset:416
	s_waitcnt vmcnt(15)
	v_lshlrev_b32_e32 v0, 16, v70
	v_and_b32_e32 v1, 0xffff0000, v70
	v_lshlrev_b32_e32 v2, 16, v71
	v_and_b32_e32 v3, 0xffff0000, v71
	v_pk_mul_f32 v[0:1], v[44:45], v[0:1] op_sel_hi:[0,1]
	v_pk_mul_f32 v[2:3], v[44:45], v[2:3] op_sel_hi:[0,1]
	s_waitcnt vmcnt(14)
	v_pk_mul_f32 v[0:1], v[32:33], v[0:1]
	v_pk_mul_f32 v[2:3], v[34:35], v[2:3]
	v_cvt_pk_bf16_f32 v0, v0, v1
	v_cvt_pk_bf16_f32 v1, v2, v3
	global_store_dwordx2 v[46:47], v[0:1], off offset:512
	s_waitcnt vmcnt(14)
	v_lshlrev_b32_e32 v0, 16, v72
	v_and_b32_e32 v1, 0xffff0000, v72
	v_lshlrev_b32_e32 v2, 16, v73
	v_and_b32_e32 v3, 0xffff0000, v73
	v_pk_mul_f32 v[0:1], v[44:45], v[0:1] op_sel_hi:[0,1]
	v_pk_mul_f32 v[2:3], v[44:45], v[2:3] op_sel_hi:[0,1]
	s_waitcnt vmcnt(13)
	v_pk_mul_f32 v[0:1], v[36:37], v[0:1]
	v_pk_mul_f32 v[2:3], v[38:39], v[2:3]
	v_cvt_pk_bf16_f32 v0, v0, v1
	v_cvt_pk_bf16_f32 v1, v2, v3
	global_store_dwordx2 v[46:47], v[0:1], off offset:544
	s_waitcnt vmcnt(13)
	v_lshlrev_b32_e32 v0, 16, v74
	v_and_b32_e32 v1, 0xffff0000, v74
	v_lshlrev_b32_e32 v2, 16, v75
	v_and_b32_e32 v3, 0xffff0000, v75
	v_pk_mul_f32 v[0:1], v[44:45], v[0:1] op_sel_hi:[0,1]
	v_pk_mul_f32 v[2:3], v[44:45], v[2:3] op_sel_hi:[0,1]
	s_waitcnt vmcnt(12)
	v_pk_mul_f32 v[0:1], v[40:41], v[0:1]
	v_pk_mul_f32 v[2:3], v[42:43], v[2:3]
	v_cvt_pk_bf16_f32 v0, v0, v1
	v_cvt_pk_bf16_f32 v1, v2, v3
	global_store_dwordx2 v[46:47], v[0:1], off offset:640
	s_waitcnt vmcnt(12)
	v_lshlrev_b32_e32 v0, 16, v76
	v_and_b32_e32 v1, 0xffff0000, v76
	v_lshlrev_b32_e32 v2, 16, v77
	v_and_b32_e32 v3, 0xffff0000, v77
	v_pk_mul_f32 v[0:1], v[44:45], v[0:1] op_sel_hi:[0,1]
	v_pk_mul_f32 v[2:3], v[44:45], v[2:3] op_sel_hi:[0,1]
	s_waitcnt vmcnt(11)
	v_pk_mul_f32 v[0:1], v[48:49], v[0:1]
	v_pk_mul_f32 v[2:3], v[50:51], v[2:3]
	v_cvt_pk_bf16_f32 v0, v0, v1
	v_cvt_pk_bf16_f32 v1, v2, v3
	global_store_dwordx2 v[46:47], v[0:1], off offset:672
	global_load_dwordx2 v[68:69], v[46:47], off offset:768
	global_load_dwordx4 v[40:43], v[134:135], off offset:1536
	global_load_dwordx2 v[66:67], v[46:47], off offset:800
	global_load_dwordx4 v[36:39], v[134:135], off offset:1600
	global_load_dwordx2 v[64:65], v[46:47], off offset:896
	global_load_dwordx4 v[32:35], v[134:135], off offset:1792
	global_load_dwordx2 v[62:63], v[46:47], off offset:928
	global_load_dwordx4 v[28:31], v[134:135], off offset:1856
	global_load_dwordx2 v[60:61], v[46:47], off offset:1024
	global_load_dwordx4 v[24:27], v[134:135], off offset:2048
	global_load_dwordx2 v[58:59], v[46:47], off offset:1056
	global_load_dwordx4 v[20:23], v[134:135], off offset:2112
	global_load_dwordx2 v[56:57], v[46:47], off offset:1152
	global_load_dwordx4 v[16:19], v[134:135], off offset:2304
	global_load_dwordx2 v[54:55], v[46:47], off offset:1184
	global_load_dwordx4 v[12:15], v[134:135], off offset:2368
	global_load_dwordx2 v[52:53], v[46:47], off offset:1280
	global_load_dwordx4 v[8:11], v[134:135], off offset:2560
	global_load_dwordx2 v[50:51], v[46:47], off offset:1312
	global_load_dwordx4 v[4:7], v[134:135], off offset:2624
	global_load_dwordx2 v[48:49], v[46:47], off offset:1408
	global_load_dwordx4 v[0:3], v[134:135], off offset:2816
	global_load_dwordx2 v[70:71], v[46:47], off offset:1440
	global_load_dwordx4 v[72:75], v[134:135], off offset:2880
	s_waitcnt vmcnt(23)
	v_lshlrev_b32_e32 v76, 16, v68
	v_and_b32_e32 v77, 0xffff0000, v68
	v_lshlrev_b32_e32 v68, 16, v69
	v_and_b32_e32 v69, 0xffff0000, v69
	v_pk_mul_f32 v[76:77], v[44:45], v[76:77] op_sel_hi:[0,1]
	v_pk_mul_f32 v[68:69], v[44:45], v[68:69] op_sel_hi:[0,1]
	s_waitcnt vmcnt(22)
	v_pk_mul_f32 v[40:41], v[40:41], v[76:77]
	v_pk_mul_f32 v[42:43], v[42:43], v[68:69]
	v_cvt_pk_bf16_f32 v40, v40, v41
	v_cvt_pk_bf16_f32 v41, v42, v43
	global_store_dwordx2 v[46:47], v[40:41], off offset:768
	s_waitcnt vmcnt(22)
	v_lshlrev_b32_e32 v40, 16, v66
	v_and_b32_e32 v41, 0xffff0000, v66
	v_pk_mul_f32 v[40:41], v[44:45], v[40:41] op_sel_hi:[0,1]
	s_waitcnt vmcnt(21)
	v_pk_mul_f32 v[36:37], v[36:37], v[40:41]
	v_lshlrev_b32_e32 v40, 16, v67
	v_and_b32_e32 v41, 0xffff0000, v67
	v_pk_mul_f32 v[40:41], v[44:45], v[40:41] op_sel_hi:[0,1]
	v_pk_mul_f32 v[38:39], v[38:39], v[40:41]
	v_cvt_pk_bf16_f32 v36, v36, v37
	v_cvt_pk_bf16_f32 v37, v38, v39
	global_store_dwordx2 v[46:47], v[36:37], off offset:800
	s_waitcnt vmcnt(21)
	v_lshlrev_b32_e32 v36, 16, v64
	v_and_b32_e32 v37, 0xffff0000, v64
	v_pk_mul_f32 v[36:37], v[44:45], v[36:37] op_sel_hi:[0,1]
	s_waitcnt vmcnt(20)
	v_pk_mul_f32 v[32:33], v[32:33], v[36:37]
	v_lshlrev_b32_e32 v36, 16, v65
	v_and_b32_e32 v37, 0xffff0000, v65
	v_pk_mul_f32 v[36:37], v[44:45], v[36:37] op_sel_hi:[0,1]
	v_pk_mul_f32 v[34:35], v[34:35], v[36:37]
	v_cvt_pk_bf16_f32 v32, v32, v33
	v_cvt_pk_bf16_f32 v33, v34, v35
	global_store_dwordx2 v[46:47], v[32:33], off offset:896
	s_waitcnt vmcnt(20)
	v_lshlrev_b32_e32 v32, 16, v62
	v_and_b32_e32 v33, 0xffff0000, v62
	v_pk_mul_f32 v[32:33], v[44:45], v[32:33] op_sel_hi:[0,1]
	s_waitcnt vmcnt(19)
	v_pk_mul_f32 v[28:29], v[28:29], v[32:33]
	v_lshlrev_b32_e32 v32, 16, v63
	v_and_b32_e32 v33, 0xffff0000, v63
	v_pk_mul_f32 v[32:33], v[44:45], v[32:33] op_sel_hi:[0,1]
	v_pk_mul_f32 v[30:31], v[30:31], v[32:33]
	v_cvt_pk_bf16_f32 v28, v28, v29
	v_cvt_pk_bf16_f32 v29, v30, v31
	global_store_dwordx2 v[46:47], v[28:29], off offset:928
	s_waitcnt vmcnt(19)
	v_lshlrev_b32_e32 v28, 16, v60
	v_and_b32_e32 v29, 0xffff0000, v60
	v_pk_mul_f32 v[28:29], v[44:45], v[28:29] op_sel_hi:[0,1]
	s_waitcnt vmcnt(18)
	v_pk_mul_f32 v[24:25], v[24:25], v[28:29]
	v_lshlrev_b32_e32 v28, 16, v61
	v_and_b32_e32 v29, 0xffff0000, v61
	v_pk_mul_f32 v[28:29], v[44:45], v[28:29] op_sel_hi:[0,1]
	v_pk_mul_f32 v[26:27], v[26:27], v[28:29]
	v_cvt_pk_bf16_f32 v24, v24, v25
	v_cvt_pk_bf16_f32 v25, v26, v27
	global_store_dwordx2 v[46:47], v[24:25], off offset:1024
	s_waitcnt vmcnt(18)
	v_lshlrev_b32_e32 v24, 16, v58
	v_and_b32_e32 v25, 0xffff0000, v58
	v_pk_mul_f32 v[24:25], v[44:45], v[24:25] op_sel_hi:[0,1]
	s_waitcnt vmcnt(17)
	v_pk_mul_f32 v[20:21], v[20:21], v[24:25]
	v_lshlrev_b32_e32 v24, 16, v59
	v_and_b32_e32 v25, 0xffff0000, v59
	v_pk_mul_f32 v[24:25], v[44:45], v[24:25] op_sel_hi:[0,1]
	v_pk_mul_f32 v[22:23], v[22:23], v[24:25]
	v_cvt_pk_bf16_f32 v20, v20, v21
	v_cvt_pk_bf16_f32 v21, v22, v23
	global_store_dwordx2 v[46:47], v[20:21], off offset:1056
	s_waitcnt vmcnt(17)
	v_lshlrev_b32_e32 v20, 16, v56
	v_and_b32_e32 v21, 0xffff0000, v56
	v_pk_mul_f32 v[20:21], v[44:45], v[20:21] op_sel_hi:[0,1]
	s_waitcnt vmcnt(16)
	v_pk_mul_f32 v[16:17], v[16:17], v[20:21]
	v_lshlrev_b32_e32 v20, 16, v57
	v_and_b32_e32 v21, 0xffff0000, v57
	v_pk_mul_f32 v[20:21], v[44:45], v[20:21] op_sel_hi:[0,1]
	v_pk_mul_f32 v[18:19], v[18:19], v[20:21]
	v_cvt_pk_bf16_f32 v16, v16, v17
	v_cvt_pk_bf16_f32 v17, v18, v19
	global_store_dwordx2 v[46:47], v[16:17], off offset:1152
	s_waitcnt vmcnt(16)
	v_lshlrev_b32_e32 v16, 16, v54
	v_and_b32_e32 v17, 0xffff0000, v54
	v_pk_mul_f32 v[16:17], v[44:45], v[16:17] op_sel_hi:[0,1]
	s_waitcnt vmcnt(15)
	v_pk_mul_f32 v[12:13], v[12:13], v[16:17]
	v_lshlrev_b32_e32 v16, 16, v55
	v_and_b32_e32 v17, 0xffff0000, v55
	v_pk_mul_f32 v[16:17], v[44:45], v[16:17] op_sel_hi:[0,1]
	v_pk_mul_f32 v[14:15], v[14:15], v[16:17]
	v_cvt_pk_bf16_f32 v12, v12, v13
	v_cvt_pk_bf16_f32 v13, v14, v15
	global_store_dwordx2 v[46:47], v[12:13], off offset:1184
	s_waitcnt vmcnt(15)
	v_lshlrev_b32_e32 v12, 16, v52
	v_and_b32_e32 v13, 0xffff0000, v52
	v_pk_mul_f32 v[12:13], v[44:45], v[12:13] op_sel_hi:[0,1]
	s_waitcnt vmcnt(14)
	v_pk_mul_f32 v[8:9], v[8:9], v[12:13]
	v_lshlrev_b32_e32 v12, 16, v53
	v_and_b32_e32 v13, 0xffff0000, v53
	v_pk_mul_f32 v[12:13], v[44:45], v[12:13] op_sel_hi:[0,1]
	v_pk_mul_f32 v[10:11], v[10:11], v[12:13]
	v_cvt_pk_bf16_f32 v8, v8, v9
	v_cvt_pk_bf16_f32 v9, v10, v11
	global_store_dwordx2 v[46:47], v[8:9], off offset:1280
	s_waitcnt vmcnt(14)
	v_lshlrev_b32_e32 v8, 16, v50
	v_and_b32_e32 v9, 0xffff0000, v50
	v_pk_mul_f32 v[8:9], v[44:45], v[8:9] op_sel_hi:[0,1]
	s_waitcnt vmcnt(13)
	v_pk_mul_f32 v[4:5], v[4:5], v[8:9]
	v_lshlrev_b32_e32 v8, 16, v51
	v_and_b32_e32 v9, 0xffff0000, v51
	v_pk_mul_f32 v[8:9], v[44:45], v[8:9] op_sel_hi:[0,1]
	v_pk_mul_f32 v[6:7], v[6:7], v[8:9]
	v_cvt_pk_bf16_f32 v4, v4, v5
	v_cvt_pk_bf16_f32 v5, v6, v7
	global_store_dwordx2 v[46:47], v[4:5], off offset:1312
	s_waitcnt vmcnt(13)
	v_lshlrev_b32_e32 v4, 16, v48
	v_and_b32_e32 v5, 0xffff0000, v48
	v_pk_mul_f32 v[4:5], v[44:45], v[4:5] op_sel_hi:[0,1]
	s_waitcnt vmcnt(12)
	v_pk_mul_f32 v[0:1], v[0:1], v[4:5]
	v_lshlrev_b32_e32 v4, 16, v49
	v_and_b32_e32 v5, 0xffff0000, v49
	v_pk_mul_f32 v[4:5], v[44:45], v[4:5] op_sel_hi:[0,1]
	v_pk_mul_f32 v[2:3], v[2:3], v[4:5]
	v_cvt_pk_bf16_f32 v0, v0, v1
	v_cvt_pk_bf16_f32 v1, v2, v3
	global_store_dwordx2 v[46:47], v[0:1], off offset:1408
	s_waitcnt vmcnt(12)
	v_lshlrev_b32_e32 v0, 16, v70
	v_and_b32_e32 v1, 0xffff0000, v70
	v_lshlrev_b32_e32 v2, 16, v71
	v_and_b32_e32 v3, 0xffff0000, v71
	v_pk_mul_f32 v[0:1], v[44:45], v[0:1] op_sel_hi:[0,1]
	v_pk_mul_f32 v[2:3], v[44:45], v[2:3] op_sel_hi:[0,1]
	s_waitcnt vmcnt(11)
	v_pk_mul_f32 v[0:1], v[72:73], v[0:1]
	v_pk_mul_f32 v[2:3], v[74:75], v[2:3]
	v_cvt_pk_bf16_f32 v0, v0, v1
	v_cvt_pk_bf16_f32 v1, v2, v3
	global_store_dwordx2 v[46:47], v[0:1], off offset:1440
	s_cmpk_eq_i32 s96, 0x100
	s_cbranch_scc0 .LBB0_817
	s_bitcmp1_b32 s97, 0
	s_cbranch_scc0 .LBB0_817
	s_branch .LBB0_883
.LBB0_817:
	s_add_u32 s0, s40, 0xdad6000
	s_addc_u32 s1, s41, 0
	s_add_u32 s8, s40, 0x10c56000
	s_addc_u32 s9, s41, 0
	v_mov_b32_e32 v96, v194
	v_lshrrev_b32_e32 v97, 5, v96
	v_mul_u32_u24_e32 v97, 0xaaab, v97
	v_lshrrev_b32_e32 v97, 17, v97
	v_mul_u32_u24_e32 v98, 0x60, v97
	v_sub_u32_e32 v98, v96, v98
	v_add_u32_e32 v97, s44, v97
	v_bfe_u32 v99, v98, 3, 2
	v_lshlrev_b32_e32 v99, 2, v99
	v_mad_u32_u24 v99, v97, 48, v99
	v_lshlrev_b32_e32 v100, 4, v98
	v_mad_u32_u24 v84, v97, s3, v100
	v_lshrrev_b32_e32 v196, 5, v98
	global_load_dword v0, v99, s[8:9]
	global_load_dword v1, v99, s[8:9] offset:16
	global_load_dword v2, v99, s[8:9] offset:32
	global_load_dwordx4 v[36:39], v84, s[0:1]
	v_add_u32_e32 v96, 0x200, v194
	v_lshrrev_b32_e32 v97, 5, v96
	v_mul_u32_u24_e32 v97, 0xaaab, v97
	v_lshrrev_b32_e32 v97, 17, v97
	v_mul_u32_u24_e32 v98, 0x60, v97
	v_sub_u32_e32 v98, v96, v98
	v_add_u32_e32 v97, s44, v97
	v_bfe_u32 v99, v98, 3, 2
	v_lshlrev_b32_e32 v99, 2, v99
	v_mad_u32_u24 v99, v97, 48, v99
	v_lshlrev_b32_e32 v100, 4, v98
	v_mad_u32_u24 v85, v97, s3, v100
	v_lshrrev_b32_e32 v197, 5, v98
	global_load_dword v3, v99, s[8:9]
	global_load_dword v4, v99, s[8:9] offset:16
	global_load_dword v5, v99, s[8:9] offset:32
	global_load_dwordx4 v[40:43], v85, s[0:1]
	v_add_u32_e32 v96, 0x400, v194
	v_lshrrev_b32_e32 v97, 5, v96
	v_mul_u32_u24_e32 v97, 0xaaab, v97
	v_lshrrev_b32_e32 v97, 17, v97
	v_mul_u32_u24_e32 v98, 0x60, v97
	v_sub_u32_e32 v98, v96, v98
	v_add_u32_e32 v97, s44, v97
	v_bfe_u32 v99, v98, 3, 2
	v_lshlrev_b32_e32 v99, 2, v99
	v_mad_u32_u24 v99, v97, 48, v99
	v_lshlrev_b32_e32 v100, 4, v98
	v_mad_u32_u24 v86, v97, s3, v100
	v_lshrrev_b32_e32 v198, 5, v98
	global_load_dword v6, v99, s[8:9]
	global_load_dword v7, v99, s[8:9] offset:16
	global_load_dword v8, v99, s[8:9] offset:32
	global_load_dwordx4 v[44:47], v86, s[0:1]
	v_add_u32_e32 v96, 0x600, v194
	v_lshrrev_b32_e32 v97, 5, v96
	v_mul_u32_u24_e32 v97, 0xaaab, v97
	v_lshrrev_b32_e32 v97, 17, v97
	v_mul_u32_u24_e32 v98, 0x60, v97
	v_sub_u32_e32 v98, v96, v98
	v_add_u32_e32 v97, s44, v97
	v_bfe_u32 v99, v98, 3, 2
	v_lshlrev_b32_e32 v99, 2, v99
	v_mad_u32_u24 v99, v97, 48, v99
	v_lshlrev_b32_e32 v100, 4, v98
	v_mad_u32_u24 v87, v97, s3, v100
	v_lshrrev_b32_e32 v199, 5, v98
	global_load_dword v9, v99, s[8:9]
	global_load_dword v10, v99, s[8:9] offset:16
	global_load_dword v11, v99, s[8:9] offset:32
	global_load_dwordx4 v[48:51], v87, s[0:1]
	v_add_u32_e32 v96, 0x800, v194
	v_lshrrev_b32_e32 v97, 5, v96
	v_mul_u32_u24_e32 v97, 0xaaab, v97
	v_lshrrev_b32_e32 v97, 17, v97
	v_mul_u32_u24_e32 v98, 0x60, v97
	v_sub_u32_e32 v98, v96, v98
	v_add_u32_e32 v97, s44, v97
	v_bfe_u32 v99, v98, 3, 2
	v_lshlrev_b32_e32 v99, 2, v99
	v_mad_u32_u24 v99, v97, 48, v99
	v_lshlrev_b32_e32 v100, 4, v98
	v_mad_u32_u24 v88, v97, s3, v100
	v_lshrrev_b32_e32 v200, 5, v98
	global_load_dword v12, v99, s[8:9]
	global_load_dword v13, v99, s[8:9] offset:16
	global_load_dword v14, v99, s[8:9] offset:32
	global_load_dwordx4 v[52:55], v88, s[0:1]
	v_add_u32_e32 v96, 0xa00, v194
	v_lshrrev_b32_e32 v97, 5, v96
	v_mul_u32_u24_e32 v97, 0xaaab, v97
	v_lshrrev_b32_e32 v97, 17, v97
	v_mul_u32_u24_e32 v98, 0x60, v97
	v_sub_u32_e32 v98, v96, v98
	v_add_u32_e32 v97, s44, v97
	v_bfe_u32 v99, v98, 3, 2
	v_lshlrev_b32_e32 v99, 2, v99
	v_mad_u32_u24 v99, v97, 48, v99
	v_lshlrev_b32_e32 v100, 4, v98
	v_mad_u32_u24 v89, v97, s3, v100
	v_lshrrev_b32_e32 v201, 5, v98
	global_load_dword v15, v99, s[8:9]
	global_load_dword v16, v99, s[8:9] offset:16
	global_load_dword v17, v99, s[8:9] offset:32
	global_load_dwordx4 v[56:59], v89, s[0:1]
	v_add_u32_e32 v96, 0xc00, v194
	v_lshrrev_b32_e32 v97, 5, v96
	v_mul_u32_u24_e32 v97, 0xaaab, v97
	v_lshrrev_b32_e32 v97, 17, v97
	v_mul_u32_u24_e32 v98, 0x60, v97
	v_sub_u32_e32 v98, v96, v98
	v_add_u32_e32 v97, s44, v97
	v_bfe_u32 v99, v98, 3, 2
	v_lshlrev_b32_e32 v99, 2, v99
	v_mad_u32_u24 v99, v97, 48, v99
	v_lshlrev_b32_e32 v100, 4, v98
	v_mad_u32_u24 v90, v97, s3, v100
	v_lshrrev_b32_e32 v202, 5, v98
	global_load_dword v18, v99, s[8:9]
	global_load_dword v19, v99, s[8:9] offset:16
	global_load_dword v20, v99, s[8:9] offset:32
	global_load_dwordx4 v[60:63], v90, s[0:1]
	v_add_u32_e32 v96, 0xe00, v194
	v_lshrrev_b32_e32 v97, 5, v96
	v_mul_u32_u24_e32 v97, 0xaaab, v97
	v_lshrrev_b32_e32 v97, 17, v97
	v_mul_u32_u24_e32 v98, 0x60, v97
	v_sub_u32_e32 v98, v96, v98
	v_add_u32_e32 v97, s44, v97
	v_bfe_u32 v99, v98, 3, 2
	v_lshlrev_b32_e32 v99, 2, v99
	v_mad_u32_u24 v99, v97, 48, v99
	v_lshlrev_b32_e32 v100, 4, v98
	v_mad_u32_u24 v91, v97, s3, v100
	v_lshrrev_b32_e32 v203, 5, v98
	global_load_dword v21, v99, s[8:9]
	global_load_dword v22, v99, s[8:9] offset:16
	global_load_dword v23, v99, s[8:9] offset:32
	global_load_dwordx4 v[64:67], v91, s[0:1]
	v_add_u32_e32 v96, 0x1000, v194
	v_lshrrev_b32_e32 v97, 5, v96
	v_mul_u32_u24_e32 v97, 0xaaab, v97
	v_lshrrev_b32_e32 v97, 17, v97
	v_mul_u32_u24_e32 v98, 0x60, v97
	v_sub_u32_e32 v98, v96, v98
	v_add_u32_e32 v97, s44, v97
	v_bfe_u32 v99, v98, 3, 2
	v_lshlrev_b32_e32 v99, 2, v99
	v_mad_u32_u24 v99, v97, 48, v99
	v_lshlrev_b32_e32 v100, 4, v98
	v_mad_u32_u24 v92, v97, s3, v100
	v_lshrrev_b32_e32 v204, 5, v98
	global_load_dword v24, v99, s[8:9]
	global_load_dword v25, v99, s[8:9] offset:16
	global_load_dword v26, v99, s[8:9] offset:32
	global_load_dwordx4 v[68:71], v92, s[0:1]
	v_add_u32_e32 v96, 0x1200, v194
	v_lshrrev_b32_e32 v97, 5, v96
	v_mul_u32_u24_e32 v97, 0xaaab, v97
	v_lshrrev_b32_e32 v97, 17, v97
	v_mul_u32_u24_e32 v98, 0x60, v97
	v_sub_u32_e32 v98, v96, v98
	v_add_u32_e32 v97, s44, v97
	v_bfe_u32 v99, v98, 3, 2
	v_lshlrev_b32_e32 v99, 2, v99
	v_mad_u32_u24 v99, v97, 48, v99
	v_lshlrev_b32_e32 v100, 4, v98
	v_mad_u32_u24 v93, v97, s3, v100
	v_lshrrev_b32_e32 v205, 5, v98
	global_load_dword v27, v99, s[8:9]
	global_load_dword v28, v99, s[8:9] offset:16
	global_load_dword v29, v99, s[8:9] offset:32
	global_load_dwordx4 v[72:75], v93, s[0:1]
	v_add_u32_e32 v96, 0x1400, v194
	v_lshrrev_b32_e32 v97, 5, v96
	v_mul_u32_u24_e32 v97, 0xaaab, v97
	v_lshrrev_b32_e32 v97, 17, v97
	v_mul_u32_u24_e32 v98, 0x60, v97
	v_sub_u32_e32 v98, v96, v98
	v_add_u32_e32 v97, s44, v97
	v_bfe_u32 v99, v98, 3, 2
	v_lshlrev_b32_e32 v99, 2, v99
	v_mad_u32_u24 v99, v97, 48, v99
	v_lshlrev_b32_e32 v100, 4, v98
	v_mad_u32_u24 v94, v97, s3, v100
	v_lshrrev_b32_e32 v206, 5, v98
	global_load_dword v30, v99, s[8:9]
	global_load_dword v31, v99, s[8:9] offset:16
	global_load_dword v32, v99, s[8:9] offset:32
	global_load_dwordx4 v[76:79], v94, s[0:1]
	v_add_u32_e32 v96, 0x1600, v194
	v_lshrrev_b32_e32 v97, 5, v96
	v_mul_u32_u24_e32 v97, 0xaaab, v97
	v_lshrrev_b32_e32 v97, 17, v97
	v_mul_u32_u24_e32 v98, 0x60, v97
	v_sub_u32_e32 v98, v96, v98
	v_add_u32_e32 v97, s44, v97
	v_bfe_u32 v99, v98, 3, 2
	v_lshlrev_b32_e32 v99, 2, v99
	v_mad_u32_u24 v99, v97, 48, v99
	v_lshlrev_b32_e32 v100, 4, v98
	v_mad_u32_u24 v95, v97, s3, v100
	v_lshrrev_b32_e32 v207, 5, v98
	global_load_dword v33, v99, s[8:9]
	global_load_dword v34, v99, s[8:9] offset:16
	global_load_dword v35, v99, s[8:9] offset:32
	global_load_dwordx4 v[80:83], v95, s[0:1]
	s_waitcnt vmcnt(44)
	v_max3_f32 v96, v0, v1, v2
	v_sub_f32_e32 v0, v0, v96
	v_sub_f32_e32 v1, v1, v96
	v_sub_f32_e32 v2, v2, v96
	v_mul_f32_e32 v0, 0x3fb8aa3b, v0
	v_mul_f32_e32 v1, 0x3fb8aa3b, v1
	v_mul_f32_e32 v2, 0x3fb8aa3b, v2
	v_exp_f32_e32 v0, v0
	v_exp_f32_e32 v1, v1
	v_exp_f32_e32 v2, v2
	v_cmp_eq_u32_e32 vcc, 1, v196
	s_nop 1
	v_cndmask_b32_e32 v97, v2, v1, vcc
	v_cmp_eq_u32_e32 vcc, 0, v196
	v_add_f32_e32 v98, v0, v1
	v_add_f32_e32 v98, v2, v98
	v_cndmask_b32_e32 v97, v97, v0, vcc
	v_div_scale_f32 v101, vcc, v97, v98, v97
	v_div_scale_f32 v99, s[8:9], v98, v98, v97
	v_rcp_f32_e32 v100, v99
	s_nop 0
	v_fma_f32 v102, -v99, v100, 1.0
	v_fmac_f32_e32 v100, v102, v100
	v_mul_f32_e32 v102, v101, v100
	v_fma_f32 v103, -v99, v102, v101
	v_fmac_f32_e32 v102, v103, v100
	v_fma_f32 v101, -v99, v102, v101
	v_div_fmas_f32 v101, v101, v100, v102
	v_div_fixup_f32 v99, v101, v98, v97
	v_lshlrev_b32_e32 v208, 16, v36
	v_and_b32_e32 v209, 0xffff0000, v36
	v_mul_f32_e32 v208, v208, v99
	v_mul_f32_e32 v209, v209, v99
	v_cvt_pk_bf16_f32 v36, v208, v209
	v_lshlrev_b32_e32 v208, 16, v37
	v_and_b32_e32 v209, 0xffff0000, v37
	v_mul_f32_e32 v208, v208, v99
	v_mul_f32_e32 v209, v209, v99
	v_cvt_pk_bf16_f32 v37, v208, v209
	v_lshlrev_b32_e32 v208, 16, v38
	v_and_b32_e32 v209, 0xffff0000, v38
	v_mul_f32_e32 v208, v208, v99
	v_mul_f32_e32 v209, v209, v99
	v_cvt_pk_bf16_f32 v38, v208, v209
	v_lshlrev_b32_e32 v208, 16, v39
	v_and_b32_e32 v209, 0xffff0000, v39
	v_mul_f32_e32 v208, v208, v99
	v_mul_f32_e32 v209, v209, v99
	v_cvt_pk_bf16_f32 v39, v208, v209
	global_store_dwordx4 v84, v[36:39], s[0:1]
	s_waitcnt vmcnt(41)
	v_max3_f32 v96, v3, v4, v5
	v_sub_f32_e32 v3, v3, v96
	v_sub_f32_e32 v4, v4, v96
	v_sub_f32_e32 v5, v5, v96
	v_mul_f32_e32 v3, 0x3fb8aa3b, v3
	v_mul_f32_e32 v4, 0x3fb8aa3b, v4
	v_mul_f32_e32 v5, 0x3fb8aa3b, v5
	v_exp_f32_e32 v3, v3
	v_exp_f32_e32 v4, v4
	v_exp_f32_e32 v5, v5
	v_cmp_eq_u32_e32 vcc, 1, v197
	s_nop 1
	v_cndmask_b32_e32 v97, v5, v4, vcc
	v_cmp_eq_u32_e32 vcc, 0, v197
	v_add_f32_e32 v98, v3, v4
	v_add_f32_e32 v98, v5, v98
	v_cndmask_b32_e32 v97, v97, v3, vcc
	v_div_scale_f32 v101, vcc, v97, v98, v97
	v_div_scale_f32 v99, s[8:9], v98, v98, v97
	v_rcp_f32_e32 v100, v99
	s_nop 0
	v_fma_f32 v102, -v99, v100, 1.0
	v_fmac_f32_e32 v100, v102, v100
	v_mul_f32_e32 v102, v101, v100
	v_fma_f32 v103, -v99, v102, v101
	v_fmac_f32_e32 v102, v103, v100
	v_fma_f32 v101, -v99, v102, v101
	v_div_fmas_f32 v101, v101, v100, v102
	v_div_fixup_f32 v99, v101, v98, v97
	v_lshlrev_b32_e32 v208, 16, v40
	v_and_b32_e32 v209, 0xffff0000, v40
	v_mul_f32_e32 v208, v208, v99
	v_mul_f32_e32 v209, v209, v99
	v_cvt_pk_bf16_f32 v40, v208, v209
	v_lshlrev_b32_e32 v208, 16, v41
	v_and_b32_e32 v209, 0xffff0000, v41
	v_mul_f32_e32 v208, v208, v99
	v_mul_f32_e32 v209, v209, v99
	v_cvt_pk_bf16_f32 v41, v208, v209
	v_lshlrev_b32_e32 v208, 16, v42
	v_and_b32_e32 v209, 0xffff0000, v42
	v_mul_f32_e32 v208, v208, v99
	v_mul_f32_e32 v209, v209, v99
	v_cvt_pk_bf16_f32 v42, v208, v209
	v_lshlrev_b32_e32 v208, 16, v43
	v_and_b32_e32 v209, 0xffff0000, v43
	v_mul_f32_e32 v208, v208, v99
	v_mul_f32_e32 v209, v209, v99
	v_cvt_pk_bf16_f32 v43, v208, v209
	global_store_dwordx4 v85, v[40:43], s[0:1]
	s_waitcnt vmcnt(38)
	v_max3_f32 v96, v6, v7, v8
	v_sub_f32_e32 v6, v6, v96
	v_sub_f32_e32 v7, v7, v96
	v_sub_f32_e32 v8, v8, v96
	v_mul_f32_e32 v6, 0x3fb8aa3b, v6
	v_mul_f32_e32 v7, 0x3fb8aa3b, v7
	v_mul_f32_e32 v8, 0x3fb8aa3b, v8
	v_exp_f32_e32 v6, v6
	v_exp_f32_e32 v7, v7
	v_exp_f32_e32 v8, v8
	v_cmp_eq_u32_e32 vcc, 1, v198
	s_nop 1
	v_cndmask_b32_e32 v97, v8, v7, vcc
	v_cmp_eq_u32_e32 vcc, 0, v198
	v_add_f32_e32 v98, v6, v7
	v_add_f32_e32 v98, v8, v98
	v_cndmask_b32_e32 v97, v97, v6, vcc
	v_div_scale_f32 v101, vcc, v97, v98, v97
	v_div_scale_f32 v99, s[8:9], v98, v98, v97
	v_rcp_f32_e32 v100, v99
	s_nop 0
	v_fma_f32 v102, -v99, v100, 1.0
	v_fmac_f32_e32 v100, v102, v100
	v_mul_f32_e32 v102, v101, v100
	v_fma_f32 v103, -v99, v102, v101
	v_fmac_f32_e32 v102, v103, v100
	v_fma_f32 v101, -v99, v102, v101
	v_div_fmas_f32 v101, v101, v100, v102
	v_div_fixup_f32 v99, v101, v98, v97
	v_lshlrev_b32_e32 v208, 16, v44
	v_and_b32_e32 v209, 0xffff0000, v44
	v_mul_f32_e32 v208, v208, v99
	v_mul_f32_e32 v209, v209, v99
	v_cvt_pk_bf16_f32 v44, v208, v209
	v_lshlrev_b32_e32 v208, 16, v45
	v_and_b32_e32 v209, 0xffff0000, v45
	v_mul_f32_e32 v208, v208, v99
	v_mul_f32_e32 v209, v209, v99
	v_cvt_pk_bf16_f32 v45, v208, v209
	v_lshlrev_b32_e32 v208, 16, v46
	v_and_b32_e32 v209, 0xffff0000, v46
	v_mul_f32_e32 v208, v208, v99
	v_mul_f32_e32 v209, v209, v99
	v_cvt_pk_bf16_f32 v46, v208, v209
	v_lshlrev_b32_e32 v208, 16, v47
	v_and_b32_e32 v209, 0xffff0000, v47
	v_mul_f32_e32 v208, v208, v99
	v_mul_f32_e32 v209, v209, v99
	v_cvt_pk_bf16_f32 v47, v208, v209
	global_store_dwordx4 v86, v[44:47], s[0:1]
	s_waitcnt vmcnt(35)
	v_max3_f32 v96, v9, v10, v11
	v_sub_f32_e32 v9, v9, v96
	v_sub_f32_e32 v10, v10, v96
	v_sub_f32_e32 v11, v11, v96
	v_mul_f32_e32 v9, 0x3fb8aa3b, v9
	v_mul_f32_e32 v10, 0x3fb8aa3b, v10
	v_mul_f32_e32 v11, 0x3fb8aa3b, v11
	v_exp_f32_e32 v9, v9
	v_exp_f32_e32 v10, v10
	v_exp_f32_e32 v11, v11
	v_cmp_eq_u32_e32 vcc, 1, v199
	s_nop 1
	v_cndmask_b32_e32 v97, v11, v10, vcc
	v_cmp_eq_u32_e32 vcc, 0, v199
	v_add_f32_e32 v98, v9, v10
	v_add_f32_e32 v98, v11, v98
	v_cndmask_b32_e32 v97, v97, v9, vcc
	v_div_scale_f32 v101, vcc, v97, v98, v97
	v_div_scale_f32 v99, s[8:9], v98, v98, v97
	v_rcp_f32_e32 v100, v99
	s_nop 0
	v_fma_f32 v102, -v99, v100, 1.0
	v_fmac_f32_e32 v100, v102, v100
	v_mul_f32_e32 v102, v101, v100
	v_fma_f32 v103, -v99, v102, v101
	v_fmac_f32_e32 v102, v103, v100
	v_fma_f32 v101, -v99, v102, v101
	v_div_fmas_f32 v101, v101, v100, v102
	v_div_fixup_f32 v99, v101, v98, v97
	v_lshlrev_b32_e32 v208, 16, v48
	v_and_b32_e32 v209, 0xffff0000, v48
	v_mul_f32_e32 v208, v208, v99
	v_mul_f32_e32 v209, v209, v99
	v_cvt_pk_bf16_f32 v48, v208, v209
	v_lshlrev_b32_e32 v208, 16, v49
	v_and_b32_e32 v209, 0xffff0000, v49
	v_mul_f32_e32 v208, v208, v99
	v_mul_f32_e32 v209, v209, v99
	v_cvt_pk_bf16_f32 v49, v208, v209
	v_lshlrev_b32_e32 v208, 16, v50
	v_and_b32_e32 v209, 0xffff0000, v50
	v_mul_f32_e32 v208, v208, v99
	v_mul_f32_e32 v209, v209, v99
	v_cvt_pk_bf16_f32 v50, v208, v209
	v_lshlrev_b32_e32 v208, 16, v51
	v_and_b32_e32 v209, 0xffff0000, v51
	v_mul_f32_e32 v208, v208, v99
	v_mul_f32_e32 v209, v209, v99
	v_cvt_pk_bf16_f32 v51, v208, v209
	global_store_dwordx4 v87, v[48:51], s[0:1]
	s_waitcnt vmcnt(32)
	v_max3_f32 v96, v12, v13, v14
	v_sub_f32_e32 v12, v12, v96
	v_sub_f32_e32 v13, v13, v96
	v_sub_f32_e32 v14, v14, v96
	v_mul_f32_e32 v12, 0x3fb8aa3b, v12
	v_mul_f32_e32 v13, 0x3fb8aa3b, v13
	v_mul_f32_e32 v14, 0x3fb8aa3b, v14
	v_exp_f32_e32 v12, v12
	v_exp_f32_e32 v13, v13
	v_exp_f32_e32 v14, v14
	v_cmp_eq_u32_e32 vcc, 1, v200
	s_nop 1
	v_cndmask_b32_e32 v97, v14, v13, vcc
	v_cmp_eq_u32_e32 vcc, 0, v200
	v_add_f32_e32 v98, v12, v13
	v_add_f32_e32 v98, v14, v98
	v_cndmask_b32_e32 v97, v97, v12, vcc
	v_div_scale_f32 v101, vcc, v97, v98, v97
	v_div_scale_f32 v99, s[8:9], v98, v98, v97
	v_rcp_f32_e32 v100, v99
	s_nop 0
	v_fma_f32 v102, -v99, v100, 1.0
	v_fmac_f32_e32 v100, v102, v100
	v_mul_f32_e32 v102, v101, v100
	v_fma_f32 v103, -v99, v102, v101
	v_fmac_f32_e32 v102, v103, v100
	v_fma_f32 v101, -v99, v102, v101
	v_div_fmas_f32 v101, v101, v100, v102
	v_div_fixup_f32 v99, v101, v98, v97
	v_lshlrev_b32_e32 v208, 16, v52
	v_and_b32_e32 v209, 0xffff0000, v52
	v_mul_f32_e32 v208, v208, v99
	v_mul_f32_e32 v209, v209, v99
	v_cvt_pk_bf16_f32 v52, v208, v209
	v_lshlrev_b32_e32 v208, 16, v53
	v_and_b32_e32 v209, 0xffff0000, v53
	v_mul_f32_e32 v208, v208, v99
	v_mul_f32_e32 v209, v209, v99
	v_cvt_pk_bf16_f32 v53, v208, v209
	v_lshlrev_b32_e32 v208, 16, v54
	v_and_b32_e32 v209, 0xffff0000, v54
	v_mul_f32_e32 v208, v208, v99
	v_mul_f32_e32 v209, v209, v99
	v_cvt_pk_bf16_f32 v54, v208, v209
	v_lshlrev_b32_e32 v208, 16, v55
	v_and_b32_e32 v209, 0xffff0000, v55
	v_mul_f32_e32 v208, v208, v99
	v_mul_f32_e32 v209, v209, v99
	v_cvt_pk_bf16_f32 v55, v208, v209
	global_store_dwordx4 v88, v[52:55], s[0:1]
	s_waitcnt vmcnt(29)
	v_max3_f32 v96, v15, v16, v17
	v_sub_f32_e32 v15, v15, v96
	v_sub_f32_e32 v16, v16, v96
	v_sub_f32_e32 v17, v17, v96
	v_mul_f32_e32 v15, 0x3fb8aa3b, v15
	v_mul_f32_e32 v16, 0x3fb8aa3b, v16
	v_mul_f32_e32 v17, 0x3fb8aa3b, v17
	v_exp_f32_e32 v15, v15
	v_exp_f32_e32 v16, v16
	v_exp_f32_e32 v17, v17
	v_cmp_eq_u32_e32 vcc, 1, v201
	s_nop 1
	v_cndmask_b32_e32 v97, v17, v16, vcc
	v_cmp_eq_u32_e32 vcc, 0, v201
	v_add_f32_e32 v98, v15, v16
	v_add_f32_e32 v98, v17, v98
	v_cndmask_b32_e32 v97, v97, v15, vcc
	v_div_scale_f32 v101, vcc, v97, v98, v97
	v_div_scale_f32 v99, s[8:9], v98, v98, v97
	v_rcp_f32_e32 v100, v99
	s_nop 0
	v_fma_f32 v102, -v99, v100, 1.0
	v_fmac_f32_e32 v100, v102, v100
	v_mul_f32_e32 v102, v101, v100
	v_fma_f32 v103, -v99, v102, v101
	v_fmac_f32_e32 v102, v103, v100
	v_fma_f32 v101, -v99, v102, v101
	v_div_fmas_f32 v101, v101, v100, v102
	v_div_fixup_f32 v99, v101, v98, v97
	v_lshlrev_b32_e32 v208, 16, v56
	v_and_b32_e32 v209, 0xffff0000, v56
	v_mul_f32_e32 v208, v208, v99
	v_mul_f32_e32 v209, v209, v99
	v_cvt_pk_bf16_f32 v56, v208, v209
	v_lshlrev_b32_e32 v208, 16, v57
	v_and_b32_e32 v209, 0xffff0000, v57
	v_mul_f32_e32 v208, v208, v99
	v_mul_f32_e32 v209, v209, v99
	v_cvt_pk_bf16_f32 v57, v208, v209
	v_lshlrev_b32_e32 v208, 16, v58
	v_and_b32_e32 v209, 0xffff0000, v58
	v_mul_f32_e32 v208, v208, v99
	v_mul_f32_e32 v209, v209, v99
	v_cvt_pk_bf16_f32 v58, v208, v209
	v_lshlrev_b32_e32 v208, 16, v59
	v_and_b32_e32 v209, 0xffff0000, v59
	v_mul_f32_e32 v208, v208, v99
	v_mul_f32_e32 v209, v209, v99
	v_cvt_pk_bf16_f32 v59, v208, v209
	global_store_dwordx4 v89, v[56:59], s[0:1]
	s_waitcnt vmcnt(26)
	v_max3_f32 v96, v18, v19, v20
	v_sub_f32_e32 v18, v18, v96
	v_sub_f32_e32 v19, v19, v96
	v_sub_f32_e32 v20, v20, v96
	v_mul_f32_e32 v18, 0x3fb8aa3b, v18
	v_mul_f32_e32 v19, 0x3fb8aa3b, v19
	v_mul_f32_e32 v20, 0x3fb8aa3b, v20
	v_exp_f32_e32 v18, v18
	v_exp_f32_e32 v19, v19
	v_exp_f32_e32 v20, v20
	v_cmp_eq_u32_e32 vcc, 1, v202
	s_nop 1
	v_cndmask_b32_e32 v97, v20, v19, vcc
	v_cmp_eq_u32_e32 vcc, 0, v202
	v_add_f32_e32 v98, v18, v19
	v_add_f32_e32 v98, v20, v98
	v_cndmask_b32_e32 v97, v97, v18, vcc
	v_div_scale_f32 v101, vcc, v97, v98, v97
	v_div_scale_f32 v99, s[8:9], v98, v98, v97
	v_rcp_f32_e32 v100, v99
	s_nop 0
	v_fma_f32 v102, -v99, v100, 1.0
	v_fmac_f32_e32 v100, v102, v100
	v_mul_f32_e32 v102, v101, v100
	v_fma_f32 v103, -v99, v102, v101
	v_fmac_f32_e32 v102, v103, v100
	v_fma_f32 v101, -v99, v102, v101
	v_div_fmas_f32 v101, v101, v100, v102
	v_div_fixup_f32 v99, v101, v98, v97
	v_lshlrev_b32_e32 v208, 16, v60
	v_and_b32_e32 v209, 0xffff0000, v60
	v_mul_f32_e32 v208, v208, v99
	v_mul_f32_e32 v209, v209, v99
	v_cvt_pk_bf16_f32 v60, v208, v209
	v_lshlrev_b32_e32 v208, 16, v61
	v_and_b32_e32 v209, 0xffff0000, v61
	v_mul_f32_e32 v208, v208, v99
	v_mul_f32_e32 v209, v209, v99
	v_cvt_pk_bf16_f32 v61, v208, v209
	v_lshlrev_b32_e32 v208, 16, v62
	v_and_b32_e32 v209, 0xffff0000, v62
	v_mul_f32_e32 v208, v208, v99
	v_mul_f32_e32 v209, v209, v99
	v_cvt_pk_bf16_f32 v62, v208, v209
	v_lshlrev_b32_e32 v208, 16, v63
	v_and_b32_e32 v209, 0xffff0000, v63
	v_mul_f32_e32 v208, v208, v99
	v_mul_f32_e32 v209, v209, v99
	v_cvt_pk_bf16_f32 v63, v208, v209
	global_store_dwordx4 v90, v[60:63], s[0:1]
	s_waitcnt vmcnt(23)
	v_max3_f32 v96, v21, v22, v23
	v_sub_f32_e32 v21, v21, v96
	v_sub_f32_e32 v22, v22, v96
	v_sub_f32_e32 v23, v23, v96
	v_mul_f32_e32 v21, 0x3fb8aa3b, v21
	v_mul_f32_e32 v22, 0x3fb8aa3b, v22
	v_mul_f32_e32 v23, 0x3fb8aa3b, v23
	v_exp_f32_e32 v21, v21
	v_exp_f32_e32 v22, v22
	v_exp_f32_e32 v23, v23
	v_cmp_eq_u32_e32 vcc, 1, v203
	s_nop 1
	v_cndmask_b32_e32 v97, v23, v22, vcc
	v_cmp_eq_u32_e32 vcc, 0, v203
	v_add_f32_e32 v98, v21, v22
	v_add_f32_e32 v98, v23, v98
	v_cndmask_b32_e32 v97, v97, v21, vcc
	v_div_scale_f32 v101, vcc, v97, v98, v97
	v_div_scale_f32 v99, s[8:9], v98, v98, v97
	v_rcp_f32_e32 v100, v99
	s_nop 0
	v_fma_f32 v102, -v99, v100, 1.0
	v_fmac_f32_e32 v100, v102, v100
	v_mul_f32_e32 v102, v101, v100
	v_fma_f32 v103, -v99, v102, v101
	v_fmac_f32_e32 v102, v103, v100
	v_fma_f32 v101, -v99, v102, v101
	v_div_fmas_f32 v101, v101, v100, v102
	v_div_fixup_f32 v99, v101, v98, v97
	v_lshlrev_b32_e32 v208, 16, v64
	v_and_b32_e32 v209, 0xffff0000, v64
	v_mul_f32_e32 v208, v208, v99
	v_mul_f32_e32 v209, v209, v99
	v_cvt_pk_bf16_f32 v64, v208, v209
	v_lshlrev_b32_e32 v208, 16, v65
	v_and_b32_e32 v209, 0xffff0000, v65
	v_mul_f32_e32 v208, v208, v99
	v_mul_f32_e32 v209, v209, v99
	v_cvt_pk_bf16_f32 v65, v208, v209
	v_lshlrev_b32_e32 v208, 16, v66
	v_and_b32_e32 v209, 0xffff0000, v66
	v_mul_f32_e32 v208, v208, v99
	v_mul_f32_e32 v209, v209, v99
	v_cvt_pk_bf16_f32 v66, v208, v209
	v_lshlrev_b32_e32 v208, 16, v67
	v_and_b32_e32 v209, 0xffff0000, v67
	v_mul_f32_e32 v208, v208, v99
	v_mul_f32_e32 v209, v209, v99
	v_cvt_pk_bf16_f32 v67, v208, v209
	global_store_dwordx4 v91, v[64:67], s[0:1]
	s_waitcnt vmcnt(20)
	v_max3_f32 v96, v24, v25, v26
	v_sub_f32_e32 v24, v24, v96
	v_sub_f32_e32 v25, v25, v96
	v_sub_f32_e32 v26, v26, v96
	v_mul_f32_e32 v24, 0x3fb8aa3b, v24
	v_mul_f32_e32 v25, 0x3fb8aa3b, v25
	v_mul_f32_e32 v26, 0x3fb8aa3b, v26
	v_exp_f32_e32 v24, v24
	v_exp_f32_e32 v25, v25
	v_exp_f32_e32 v26, v26
	v_cmp_eq_u32_e32 vcc, 1, v204
	s_nop 1
	v_cndmask_b32_e32 v97, v26, v25, vcc
	v_cmp_eq_u32_e32 vcc, 0, v204
	v_add_f32_e32 v98, v24, v25
	v_add_f32_e32 v98, v26, v98
	v_cndmask_b32_e32 v97, v97, v24, vcc
	v_div_scale_f32 v101, vcc, v97, v98, v97
	v_div_scale_f32 v99, s[8:9], v98, v98, v97
	v_rcp_f32_e32 v100, v99
	s_nop 0
	v_fma_f32 v102, -v99, v100, 1.0
	v_fmac_f32_e32 v100, v102, v100
	v_mul_f32_e32 v102, v101, v100
	v_fma_f32 v103, -v99, v102, v101
	v_fmac_f32_e32 v102, v103, v100
	v_fma_f32 v101, -v99, v102, v101
	v_div_fmas_f32 v101, v101, v100, v102
	v_div_fixup_f32 v99, v101, v98, v97
	v_lshlrev_b32_e32 v208, 16, v68
	v_and_b32_e32 v209, 0xffff0000, v68
	v_mul_f32_e32 v208, v208, v99
	v_mul_f32_e32 v209, v209, v99
	v_cvt_pk_bf16_f32 v68, v208, v209
	v_lshlrev_b32_e32 v208, 16, v69
	v_and_b32_e32 v209, 0xffff0000, v69
	v_mul_f32_e32 v208, v208, v99
	v_mul_f32_e32 v209, v209, v99
	v_cvt_pk_bf16_f32 v69, v208, v209
	v_lshlrev_b32_e32 v208, 16, v70
	v_and_b32_e32 v209, 0xffff0000, v70
	v_mul_f32_e32 v208, v208, v99
	v_mul_f32_e32 v209, v209, v99
	v_cvt_pk_bf16_f32 v70, v208, v209
	v_lshlrev_b32_e32 v208, 16, v71
	v_and_b32_e32 v209, 0xffff0000, v71
	v_mul_f32_e32 v208, v208, v99
	v_mul_f32_e32 v209, v209, v99
	v_cvt_pk_bf16_f32 v71, v208, v209
	global_store_dwordx4 v92, v[68:71], s[0:1]
	s_waitcnt vmcnt(17)
	v_max3_f32 v96, v27, v28, v29
	v_sub_f32_e32 v27, v27, v96
	v_sub_f32_e32 v28, v28, v96
	v_sub_f32_e32 v29, v29, v96
	v_mul_f32_e32 v27, 0x3fb8aa3b, v27
	v_mul_f32_e32 v28, 0x3fb8aa3b, v28
	v_mul_f32_e32 v29, 0x3fb8aa3b, v29
	v_exp_f32_e32 v27, v27
	v_exp_f32_e32 v28, v28
	v_exp_f32_e32 v29, v29
	v_cmp_eq_u32_e32 vcc, 1, v205
	s_nop 1
	v_cndmask_b32_e32 v97, v29, v28, vcc
	v_cmp_eq_u32_e32 vcc, 0, v205
	v_add_f32_e32 v98, v27, v28
	v_add_f32_e32 v98, v29, v98
	v_cndmask_b32_e32 v97, v97, v27, vcc
	v_div_scale_f32 v101, vcc, v97, v98, v97
	v_div_scale_f32 v99, s[8:9], v98, v98, v97
	v_rcp_f32_e32 v100, v99
	s_nop 0
	v_fma_f32 v102, -v99, v100, 1.0
	v_fmac_f32_e32 v100, v102, v100
	v_mul_f32_e32 v102, v101, v100
	v_fma_f32 v103, -v99, v102, v101
	v_fmac_f32_e32 v102, v103, v100
	v_fma_f32 v101, -v99, v102, v101
	v_div_fmas_f32 v101, v101, v100, v102
	v_div_fixup_f32 v99, v101, v98, v97
	v_lshlrev_b32_e32 v208, 16, v72
	v_and_b32_e32 v209, 0xffff0000, v72
	v_mul_f32_e32 v208, v208, v99
	v_mul_f32_e32 v209, v209, v99
	v_cvt_pk_bf16_f32 v72, v208, v209
	v_lshlrev_b32_e32 v208, 16, v73
	v_and_b32_e32 v209, 0xffff0000, v73
	v_mul_f32_e32 v208, v208, v99
	v_mul_f32_e32 v209, v209, v99
	v_cvt_pk_bf16_f32 v73, v208, v209
	v_lshlrev_b32_e32 v208, 16, v74
	v_and_b32_e32 v209, 0xffff0000, v74
	v_mul_f32_e32 v208, v208, v99
	v_mul_f32_e32 v209, v209, v99
	v_cvt_pk_bf16_f32 v74, v208, v209
	v_lshlrev_b32_e32 v208, 16, v75
	v_and_b32_e32 v209, 0xffff0000, v75
	v_mul_f32_e32 v208, v208, v99
	v_mul_f32_e32 v209, v209, v99
	v_cvt_pk_bf16_f32 v75, v208, v209
	global_store_dwordx4 v93, v[72:75], s[0:1]
	s_waitcnt vmcnt(14)
	v_max3_f32 v96, v30, v31, v32
	v_sub_f32_e32 v30, v30, v96
	v_sub_f32_e32 v31, v31, v96
	v_sub_f32_e32 v32, v32, v96
	v_mul_f32_e32 v30, 0x3fb8aa3b, v30
	v_mul_f32_e32 v31, 0x3fb8aa3b, v31
	v_mul_f32_e32 v32, 0x3fb8aa3b, v32
	v_exp_f32_e32 v30, v30
	v_exp_f32_e32 v31, v31
	v_exp_f32_e32 v32, v32
	v_cmp_eq_u32_e32 vcc, 1, v206
	s_nop 1
	v_cndmask_b32_e32 v97, v32, v31, vcc
	v_cmp_eq_u32_e32 vcc, 0, v206
	v_add_f32_e32 v98, v30, v31
	v_add_f32_e32 v98, v32, v98
	v_cndmask_b32_e32 v97, v97, v30, vcc
	v_div_scale_f32 v101, vcc, v97, v98, v97
	v_div_scale_f32 v99, s[8:9], v98, v98, v97
	v_rcp_f32_e32 v100, v99
	s_nop 0
	v_fma_f32 v102, -v99, v100, 1.0
	v_fmac_f32_e32 v100, v102, v100
	v_mul_f32_e32 v102, v101, v100
	v_fma_f32 v103, -v99, v102, v101
	v_fmac_f32_e32 v102, v103, v100
	v_fma_f32 v101, -v99, v102, v101
	v_div_fmas_f32 v101, v101, v100, v102
	v_div_fixup_f32 v99, v101, v98, v97
	v_lshlrev_b32_e32 v208, 16, v76
	v_and_b32_e32 v209, 0xffff0000, v76
	v_mul_f32_e32 v208, v208, v99
	v_mul_f32_e32 v209, v209, v99
	v_cvt_pk_bf16_f32 v76, v208, v209
	v_lshlrev_b32_e32 v208, 16, v77
	v_and_b32_e32 v209, 0xffff0000, v77
	v_mul_f32_e32 v208, v208, v99
	v_mul_f32_e32 v209, v209, v99
	v_cvt_pk_bf16_f32 v77, v208, v209
	v_lshlrev_b32_e32 v208, 16, v78
	v_and_b32_e32 v209, 0xffff0000, v78
	v_mul_f32_e32 v208, v208, v99
	v_mul_f32_e32 v209, v209, v99
	v_cvt_pk_bf16_f32 v78, v208, v209
	v_lshlrev_b32_e32 v208, 16, v79
	v_and_b32_e32 v209, 0xffff0000, v79
	v_mul_f32_e32 v208, v208, v99
	v_mul_f32_e32 v209, v209, v99
	v_cvt_pk_bf16_f32 v79, v208, v209
	global_store_dwordx4 v94, v[76:79], s[0:1]
	s_waitcnt vmcnt(11)
	v_max3_f32 v96, v33, v34, v35
	v_sub_f32_e32 v33, v33, v96
	v_sub_f32_e32 v34, v34, v96
	v_sub_f32_e32 v35, v35, v96
	v_mul_f32_e32 v33, 0x3fb8aa3b, v33
	v_mul_f32_e32 v34, 0x3fb8aa3b, v34
	v_mul_f32_e32 v35, 0x3fb8aa3b, v35
	v_exp_f32_e32 v33, v33
	v_exp_f32_e32 v34, v34
	v_exp_f32_e32 v35, v35
	v_cmp_eq_u32_e32 vcc, 1, v207
	s_nop 1
	v_cndmask_b32_e32 v97, v35, v34, vcc
	v_cmp_eq_u32_e32 vcc, 0, v207
	v_add_f32_e32 v98, v33, v34
	v_add_f32_e32 v98, v35, v98
	v_cndmask_b32_e32 v97, v97, v33, vcc
	v_div_scale_f32 v101, vcc, v97, v98, v97
	v_div_scale_f32 v99, s[8:9], v98, v98, v97
	v_rcp_f32_e32 v100, v99
	s_nop 0
	v_fma_f32 v102, -v99, v100, 1.0
	v_fmac_f32_e32 v100, v102, v100
	v_mul_f32_e32 v102, v101, v100
	v_fma_f32 v103, -v99, v102, v101
	v_fmac_f32_e32 v102, v103, v100
	v_fma_f32 v101, -v99, v102, v101
	v_div_fmas_f32 v101, v101, v100, v102
	v_div_fixup_f32 v99, v101, v98, v97
	v_lshlrev_b32_e32 v208, 16, v80
	v_and_b32_e32 v209, 0xffff0000, v80
	v_mul_f32_e32 v208, v208, v99
	v_mul_f32_e32 v209, v209, v99
	v_cvt_pk_bf16_f32 v80, v208, v209
	v_lshlrev_b32_e32 v208, 16, v81
	v_and_b32_e32 v209, 0xffff0000, v81
	v_mul_f32_e32 v208, v208, v99
	v_mul_f32_e32 v209, v209, v99
	v_cvt_pk_bf16_f32 v81, v208, v209
	v_lshlrev_b32_e32 v208, 16, v82
	v_and_b32_e32 v209, 0xffff0000, v82
	v_mul_f32_e32 v208, v208, v99
	v_mul_f32_e32 v209, v209, v99
	v_cvt_pk_bf16_f32 v82, v208, v209
	v_lshlrev_b32_e32 v208, 16, v83
	v_and_b32_e32 v209, 0xffff0000, v83
	v_mul_f32_e32 v208, v208, v99
	v_mul_f32_e32 v209, v209, v99
	v_cvt_pk_bf16_f32 v83, v208, v209
	global_store_dwordx4 v95, v[80:83], s[0:1]
	s_add_i32 s49, s49, s96
	s_cmpk_eq_i32 s96, 0x100
	s_cbranch_scc0 .Lp4_keep
	s_cmpk_lt_i32 s49, 0x200
	s_cbranch_scc0 .Lp4_s2
	s_add_i32 s49, s97, 0x401
	s_branch .Lp4_keep
.Lp4_s2:
	s_cmpk_lt_i32 s49, 0x500
	s_cbranch_scc1 .Lp4_exit
	s_cmpk_gt_i32 s97, 15
	s_cbranch_scc1 .Lp4_exit
	s_lshr_b32 s49, s97, 1
	s_addk_i32 s49, 0x100
	s_branch .Lp4_keep

.Lp4_keep:
	v_readlane_b32 s0, v255, 1
	v_readlane_b32 s1, v255, 2
	s_nop 0
	s_xor_b64 s[14:15], s[14:15], s[0:1]
	s_cmpk_lt_i32 s49, 0x108
	s_cbranch_scc1 .LBB0_818
	s_cmpk_ge_i32 s49, 0x400
	s_cbranch_scc0 .LBB0_883
.LBB0_818:
	s_cmpk_gt_i32 s49, 0xff
	s_mov_b64 s[8:9], -1
	s_cbranch_scc0 .LBB0_820
	s_and_b32 s22, s49, 0x3ff
	s_lshl_b32 s22, s22, 6
	s_mov_b64 s[8:9], 0
	s_mov_b64 s[44:45], s[22:23]
